# remaining per-tile accumulator zeroing done with 64 v_mov_b64 instead of 127 v_mov_b32
# speedup vs baseline: 1.0236x; 1.0099x over previous
;     ...
; #pragma unroll
;         for (int a = 0; a < 2; ++a)
; #pragma unroll
;             for (int b = 0; b < 2; ++b)
; #pragma unroll
;                 for (int m = 0; m < 4; ++m)
; #pragma unroll
;                     for (int n = 0; n < 2; ++n) acc[a][b][m][n] = (f32x4){0.f, 0.f, 0.f, 0.f};
;         cur = nxt; cA = nA; cB = nB; ++ui;
.LBB0_82:
	s_andn2_b64 vcc, exec, s[24:25]
	s_waitcnt lgkmcnt(0)
	s_cbranch_vccnz .Lzskip_0
	s_add_u32 s14, s4, 0x100
	v_mov_b64_e32 v[0:1], 0
	v_mov_b64_e32 v[2:3], 0
	v_mov_b64_e32 v[4:5], 0
	v_mov_b64_e32 v[6:7], 0
	v_mov_b64_e32 v[8:9], 0
	v_mov_b64_e32 v[10:11], 0
	v_mov_b64_e32 v[12:13], 0
	v_mov_b64_e32 v[14:15], 0
	v_mov_b64_e32 v[16:17], 0
	v_mov_b64_e32 v[18:19], 0
	v_mov_b64_e32 v[20:21], 0
	v_mov_b64_e32 v[22:23], 0
	v_mov_b64_e32 v[24:25], 0
	v_mov_b64_e32 v[26:27], 0
	v_mov_b64_e32 v[28:29], 0
	v_mov_b64_e32 v[30:31], 0
	v_mov_b64_e32 v[32:33], 0
	v_mov_b64_e32 v[34:35], 0
	v_mov_b64_e32 v[36:37], 0
	v_mov_b64_e32 v[38:39], 0
	v_mov_b64_e32 v[40:41], 0
	v_mov_b64_e32 v[42:43], 0
	v_mov_b64_e32 v[44:45], 0
	v_mov_b64_e32 v[46:47], 0
	v_mov_b64_e32 v[48:49], 0
	v_mov_b64_e32 v[50:51], 0
	v_mov_b64_e32 v[52:53], 0
	v_mov_b64_e32 v[54:55], 0
	v_mov_b64_e32 v[56:57], 0
	v_mov_b64_e32 v[58:59], 0
	v_mov_b64_e32 v[60:61], 0
	v_mov_b64_e32 v[62:63], 0
	v_mov_b64_e32 v[64:65], 0
	v_mov_b64_e32 v[66:67], 0
	v_mov_b64_e32 v[68:69], 0
	v_mov_b64_e32 v[70:71], 0
	v_mov_b64_e32 v[72:73], 0
	v_mov_b64_e32 v[74:75], 0
	v_mov_b64_e32 v[76:77], 0
	v_mov_b64_e32 v[78:79], 0
	v_mov_b64_e32 v[80:81], 0
	v_mov_b64_e32 v[82:83], 0
	v_mov_b64_e32 v[84:85], 0
	v_mov_b64_e32 v[86:87], 0
	v_mov_b64_e32 v[88:89], 0
	v_mov_b64_e32 v[90:91], 0
	v_mov_b64_e32 v[92:93], 0
	v_mov_b64_e32 v[94:95], 0
	v_mov_b64_e32 v[96:97], 0
	v_mov_b64_e32 v[98:99], 0
	v_mov_b64_e32 v[100:101], 0
	v_mov_b64_e32 v[102:103], 0
	v_mov_b64_e32 v[104:105], 0
	v_mov_b64_e32 v[106:107], 0
	v_mov_b64_e32 v[108:109], 0
	v_mov_b64_e32 v[110:111], 0
	v_mov_b64_e32 v[112:113], 0
	v_mov_b64_e32 v[114:115], 0
	v_mov_b64_e32 v[116:117], 0
	v_mov_b64_e32 v[118:119], 0
	v_mov_b64_e32 v[120:121], 0
	v_mov_b64_e32 v[122:123], 0
	v_mov_b64_e32 v[124:125], 0
	v_mov_b64_e32 v[126:127], 0
	s_addc_u32 s15, s5, 0
	s_mov_b32 s8, 0
	s_mov_b64 s[58:59], 0x80

;     ...
; #pragma unroll
;         for (int a = 0; a < 2; ++a)
; #pragma unroll
;             for (int b = 0; b < 2; ++b)
; #pragma unroll
;                 for (int m = 0; m < 4; ++m)
; #pragma unroll
;                     for (int n = 0; n < 2; ++n) acc[a][b][m][n] = (f32x4){0.f, 0.f, 0.f, 0.f};
;         cur = nxt; cA = nA; cB = nB; ++ui;
.LBB0_131:
	s_andn2_b64 vcc, exec, s[28:29]
	s_cbranch_vccnz .Lzskip_1
	s_add_u32 s7, s2, 0x100
	v_mov_b64_e32 v[0:1], 0
	v_mov_b64_e32 v[2:3], 0
	v_mov_b64_e32 v[4:5], 0
	v_mov_b64_e32 v[6:7], 0
	v_mov_b64_e32 v[8:9], 0
	v_mov_b64_e32 v[10:11], 0
	v_mov_b64_e32 v[12:13], 0
	v_mov_b64_e32 v[14:15], 0
	v_mov_b64_e32 v[16:17], 0
	v_mov_b64_e32 v[18:19], 0
	v_mov_b64_e32 v[20:21], 0
	v_mov_b64_e32 v[22:23], 0
	v_mov_b64_e32 v[24:25], 0
	v_mov_b64_e32 v[26:27], 0
	v_mov_b64_e32 v[28:29], 0
	v_mov_b64_e32 v[30:31], 0
	v_mov_b64_e32 v[32:33], 0
	v_mov_b64_e32 v[34:35], 0
	v_mov_b64_e32 v[36:37], 0
	v_mov_b64_e32 v[38:39], 0
	v_mov_b64_e32 v[40:41], 0
	v_mov_b64_e32 v[42:43], 0
	v_mov_b64_e32 v[44:45], 0
	v_mov_b64_e32 v[46:47], 0
	v_mov_b64_e32 v[48:49], 0
	v_mov_b64_e32 v[50:51], 0
	v_mov_b64_e32 v[52:53], 0
	v_mov_b64_e32 v[54:55], 0
	v_mov_b64_e32 v[56:57], 0
	v_mov_b64_e32 v[58:59], 0
	v_mov_b64_e32 v[60:61], 0
	v_mov_b64_e32 v[62:63], 0
	v_mov_b64_e32 v[64:65], 0
	v_mov_b64_e32 v[66:67], 0
	v_mov_b64_e32 v[68:69], 0
	v_mov_b64_e32 v[70:71], 0
	v_mov_b64_e32 v[72:73], 0
	v_mov_b64_e32 v[74:75], 0
	v_mov_b64_e32 v[76:77], 0
	v_mov_b64_e32 v[78:79], 0
	v_mov_b64_e32 v[80:81], 0
	v_mov_b64_e32 v[82:83], 0
	v_mov_b64_e32 v[84:85], 0
	v_mov_b64_e32 v[86:87], 0
	v_mov_b64_e32 v[88:89], 0
	v_mov_b64_e32 v[90:91], 0
	v_mov_b64_e32 v[92:93], 0
	v_mov_b64_e32 v[94:95], 0
	v_mov_b64_e32 v[96:97], 0
	v_mov_b64_e32 v[98:99], 0
	v_mov_b64_e32 v[100:101], 0
	v_mov_b64_e32 v[102:103], 0
	v_mov_b64_e32 v[104:105], 0
	v_mov_b64_e32 v[106:107], 0
	v_mov_b64_e32 v[108:109], 0
	v_mov_b64_e32 v[110:111], 0
	v_mov_b64_e32 v[112:113], 0
	v_mov_b64_e32 v[114:115], 0
	v_mov_b64_e32 v[116:117], 0
	v_mov_b64_e32 v[118:119], 0
	v_mov_b64_e32 v[120:121], 0
	v_mov_b64_e32 v[122:123], 0
	v_mov_b64_e32 v[124:125], 0
	v_mov_b64_e32 v[126:127], 0
	v_mov_b64_e32 v[212:213], 0x77f
	v_mov_b64_e32 v[154:155], 0x780
	s_addc_u32 s8, s3, 0
	s_mov_b32 s4, 0
	s_mov_b64 s[58:59], 0x80

;     ...
; #pragma unroll
;         for (int a = 0; a < 2; ++a)
; #pragma unroll
;             for (int b = 0; b < 2; ++b)
; #pragma unroll
;                 for (int m = 0; m < 4; ++m)
; #pragma unroll
;                     for (int n = 0; n < 2; ++n) acc[a][b][m][n] = (f32x4){0.f, 0.f, 0.f, 0.f};
;         cur = nxt; cA = nA; cB = nB; ++ui;
.LBB0_204:
	s_ashr_i32 s17, s16, 31
	s_lshl_b64 s[22:23], s[16:17], 19
	v_readlane_b32 s52, v254, 28
	v_readlane_b32 s53, v254, 29
	s_add_u32 s22, s52, s22
	s_addc_u32 s23, s53, s23
	s_andn2_b64 vcc, exec, s[8:9]
	s_cbranch_vccnz .Lzskip_2
	s_and_b64 s[12:13], s[12:13], exec
	s_cselect_b32 s17, s23, s29
	s_cselect_b32 s52, s22, s28
	s_add_u32 s12, s28, 0x40080
	s_addc_u32 s13, s29, 0
	s_add_u32 s28, s26, 0x100
	v_mov_b64_e32 v[0:1], 0
	v_mov_b64_e32 v[2:3], 0
	v_mov_b64_e32 v[4:5], 0
	v_mov_b64_e32 v[6:7], 0
	v_mov_b64_e32 v[8:9], 0
	v_mov_b64_e32 v[10:11], 0
	v_mov_b64_e32 v[12:13], 0
	v_mov_b64_e32 v[14:15], 0
	v_mov_b64_e32 v[16:17], 0
	v_mov_b64_e32 v[18:19], 0
	v_mov_b64_e32 v[20:21], 0
	v_mov_b64_e32 v[22:23], 0
	v_mov_b64_e32 v[24:25], 0
	v_mov_b64_e32 v[26:27], 0
	v_mov_b64_e32 v[28:29], 0
	v_mov_b64_e32 v[30:31], 0
	v_mov_b64_e32 v[32:33], 0
	v_mov_b64_e32 v[34:35], 0
	v_mov_b64_e32 v[36:37], 0
	v_mov_b64_e32 v[38:39], 0
	v_mov_b64_e32 v[40:41], 0
	v_mov_b64_e32 v[42:43], 0
	v_mov_b64_e32 v[44:45], 0
	v_mov_b64_e32 v[46:47], 0
	v_mov_b64_e32 v[48:49], 0
	v_mov_b64_e32 v[50:51], 0
	v_mov_b64_e32 v[52:53], 0
	v_mov_b64_e32 v[54:55], 0
	v_mov_b64_e32 v[56:57], 0
	v_mov_b64_e32 v[58:59], 0
	v_mov_b64_e32 v[60:61], 0
	v_mov_b64_e32 v[62:63], 0
	v_mov_b64_e32 v[64:65], 0
	v_mov_b64_e32 v[66:67], 0
	v_mov_b64_e32 v[68:69], 0
	v_mov_b64_e32 v[70:71], 0
	v_mov_b64_e32 v[72:73], 0
	v_mov_b64_e32 v[74:75], 0
	v_mov_b64_e32 v[76:77], 0
	v_mov_b64_e32 v[78:79], 0
	v_mov_b64_e32 v[80:81], 0
	v_mov_b64_e32 v[82:83], 0
	v_mov_b64_e32 v[84:85], 0
	v_mov_b64_e32 v[86:87], 0
	v_mov_b64_e32 v[88:89], 0
	v_mov_b64_e32 v[90:91], 0
	v_mov_b64_e32 v[92:93], 0
	v_mov_b64_e32 v[94:95], 0
	v_mov_b64_e32 v[96:97], 0
	v_mov_b64_e32 v[98:99], 0
	v_mov_b64_e32 v[100:101], 0
	v_mov_b64_e32 v[102:103], 0
	v_mov_b64_e32 v[104:105], 0
	v_mov_b64_e32 v[106:107], 0
	v_mov_b64_e32 v[108:109], 0
	v_mov_b64_e32 v[110:111], 0
	v_mov_b64_e32 v[112:113], 0
	v_mov_b64_e32 v[114:115], 0
	v_mov_b64_e32 v[116:117], 0
	v_mov_b64_e32 v[118:119], 0
	v_mov_b64_e32 v[120:121], 0
	v_mov_b64_e32 v[122:123], 0
	v_mov_b64_e32 v[124:125], 0
	v_mov_b64_e32 v[126:127], 0
	s_addc_u32 s29, s27, 0
	s_mov_b32 s26, 0
	s_mov_b64 s[58:59], 0x80

;     ...
; #pragma unroll
;         for (int a = 0; a < 2; ++a)
; #pragma unroll
;             for (int b = 0; b < 2; ++b)
; #pragma unroll
;                 for (int m = 0; m < 4; ++m)
; #pragma unroll
;                     for (int n = 0; n < 2; ++n) acc[a][b][m][n] = (f32x4){0.f, 0.f, 0.f, 0.f};
;         cur = nxt; cA = nA; cB = nB; ++ui;
.LBB0_283:
	s_ashr_i32 s19, s18, 31
	s_lshl_b64 s[24:25], s[18:19], 18
	s_add_u32 s19, s38, s24
	s_addc_u32 s53, s39, s25
	s_lshl_b64 s[24:25], s[16:17], 8
	s_add_u32 s24, s19, s24
	s_addc_u32 s25, s53, s25
	s_andn2_b64 vcc, exec, s[4:5]
	s_cbranch_vccnz .Lzskip_4
	s_and_b64 s[12:13], s[12:13], exec
	s_cselect_b32 s17, s25, s31
	s_cselect_b32 s19, s24, s30
	s_add_u32 s12, s30, 0x20080
	s_addc_u32 s13, s31, 0
	s_add_u32 s30, s28, 0x100
	v_mov_b64_e32 v[0:1], 0
	v_mov_b64_e32 v[2:3], 0
	v_mov_b64_e32 v[4:5], 0
	v_mov_b64_e32 v[6:7], 0
	v_mov_b64_e32 v[8:9], 0
	v_mov_b64_e32 v[10:11], 0
	v_mov_b64_e32 v[12:13], 0
	v_mov_b64_e32 v[14:15], 0
	v_mov_b64_e32 v[16:17], 0
	v_mov_b64_e32 v[18:19], 0
	v_mov_b64_e32 v[20:21], 0
	v_mov_b64_e32 v[22:23], 0
	v_mov_b64_e32 v[24:25], 0
	v_mov_b64_e32 v[26:27], 0
	v_mov_b64_e32 v[28:29], 0
	v_mov_b64_e32 v[30:31], 0
	v_mov_b64_e32 v[32:33], 0
	v_mov_b64_e32 v[34:35], 0
	v_mov_b64_e32 v[36:37], 0
	v_mov_b64_e32 v[38:39], 0
	v_mov_b64_e32 v[40:41], 0
	v_mov_b64_e32 v[42:43], 0
	v_mov_b64_e32 v[44:45], 0
	v_mov_b64_e32 v[46:47], 0
	v_mov_b64_e32 v[48:49], 0
	v_mov_b64_e32 v[50:51], 0
	v_mov_b64_e32 v[52:53], 0
	v_mov_b64_e32 v[54:55], 0
	v_mov_b64_e32 v[56:57], 0
	v_mov_b64_e32 v[58:59], 0
	v_mov_b64_e32 v[60:61], 0
	v_mov_b64_e32 v[62:63], 0
	v_mov_b64_e32 v[64:65], 0
	v_mov_b64_e32 v[66:67], 0
	v_mov_b64_e32 v[68:69], 0
	v_mov_b64_e32 v[70:71], 0
	v_mov_b64_e32 v[72:73], 0
	v_mov_b64_e32 v[74:75], 0
	v_mov_b64_e32 v[76:77], 0
	v_mov_b64_e32 v[78:79], 0
	v_mov_b64_e32 v[80:81], 0
	v_mov_b64_e32 v[82:83], 0
	v_mov_b64_e32 v[84:85], 0
	v_mov_b64_e32 v[86:87], 0
	v_mov_b64_e32 v[88:89], 0
	v_mov_b64_e32 v[90:91], 0
	v_mov_b64_e32 v[92:93], 0
	v_mov_b64_e32 v[94:95], 0
	v_mov_b64_e32 v[96:97], 0
	v_mov_b64_e32 v[98:99], 0
	v_mov_b64_e32 v[100:101], 0
	v_mov_b64_e32 v[102:103], 0
	v_mov_b64_e32 v[104:105], 0
	v_mov_b64_e32 v[106:107], 0
	v_mov_b64_e32 v[108:109], 0
	v_mov_b64_e32 v[110:111], 0
	v_mov_b64_e32 v[120:121], 0
	v_mov_b64_e32 v[122:123], 0
	v_mov_b64_e32 v[124:125], 0
	v_mov_b64_e32 v[126:127], 0
	v_mov_b64_e32 v[128:129], 0
	v_mov_b64_e32 v[130:131], 0
	v_mov_b64_e32 v[132:133], 0
	v_mov_b64_e32 v[134:135], 0
	s_addc_u32 s31, s29, 0
	s_mov_b32 s28, 0
	s_mov_b64 s[58:59], 0x80

;     ...
; #pragma unroll
;         for (int a = 0; a < 2; ++a)
; #pragma unroll
;             for (int b = 0; b < 2; ++b)
; #pragma unroll
;                 for (int m = 0; m < 4; ++m)
; #pragma unroll
;                     for (int n = 0; n < 2; ++n) acc[a][b][m][n] = (f32x4){0.f, 0.f, 0.f, 0.f};
;         cur = nxt; cA = nA; cB = nB; ++ui;
.LBB0_312:
	s_andn2_b64 vcc, exec, s[22:23]
	s_cbranch_vccnz .Lzskip_5
	s_add_u32 s48, s2, 0x100
	v_mov_b64_e32 v[0:1], 0
	v_mov_b64_e32 v[2:3], 0
	v_mov_b64_e32 v[4:5], 0
	v_mov_b64_e32 v[6:7], 0
	v_mov_b64_e32 v[8:9], 0
	v_mov_b64_e32 v[10:11], 0
	v_mov_b64_e32 v[12:13], 0
	v_mov_b64_e32 v[14:15], 0
	v_mov_b64_e32 v[16:17], 0
	v_mov_b64_e32 v[18:19], 0
	v_mov_b64_e32 v[20:21], 0
	v_mov_b64_e32 v[22:23], 0
	v_mov_b64_e32 v[24:25], 0
	v_mov_b64_e32 v[26:27], 0
	v_mov_b64_e32 v[28:29], 0
	v_mov_b64_e32 v[30:31], 0
	v_mov_b64_e32 v[32:33], 0
	v_mov_b64_e32 v[34:35], 0
	v_mov_b64_e32 v[36:37], 0
	v_mov_b64_e32 v[38:39], 0
	v_mov_b64_e32 v[40:41], 0
	v_mov_b64_e32 v[42:43], 0
	v_mov_b64_e32 v[44:45], 0
	v_mov_b64_e32 v[46:47], 0
	v_mov_b64_e32 v[48:49], 0
	v_mov_b64_e32 v[50:51], 0
	v_mov_b64_e32 v[52:53], 0
	v_mov_b64_e32 v[54:55], 0
	v_mov_b64_e32 v[56:57], 0
	v_mov_b64_e32 v[58:59], 0
	v_mov_b64_e32 v[60:61], 0
	v_mov_b64_e32 v[62:63], 0
	v_mov_b64_e32 v[64:65], 0
	v_mov_b64_e32 v[66:67], 0
	v_mov_b64_e32 v[68:69], 0
	v_mov_b64_e32 v[70:71], 0
	v_mov_b64_e32 v[72:73], 0
	v_mov_b64_e32 v[74:75], 0
	v_mov_b64_e32 v[76:77], 0
	v_mov_b64_e32 v[78:79], 0
	v_mov_b64_e32 v[80:81], 0
	v_mov_b64_e32 v[82:83], 0
	v_mov_b64_e32 v[84:85], 0
	v_mov_b64_e32 v[86:87], 0
	v_mov_b64_e32 v[88:89], 0
	v_mov_b64_e32 v[90:91], 0
	v_mov_b64_e32 v[92:93], 0
	v_mov_b64_e32 v[94:95], 0
	v_mov_b64_e32 v[96:97], 0
	v_mov_b64_e32 v[98:99], 0
	v_mov_b64_e32 v[100:101], 0
	v_mov_b64_e32 v[102:103], 0
	v_mov_b64_e32 v[104:105], 0
	v_mov_b64_e32 v[106:107], 0
	v_mov_b64_e32 v[108:109], 0
	v_mov_b64_e32 v[110:111], 0
	v_mov_b64_e32 v[112:113], 0
	v_mov_b64_e32 v[114:115], 0
	v_mov_b64_e32 v[116:117], 0
	v_mov_b64_e32 v[118:119], 0
	v_mov_b64_e32 v[120:121], 0
	v_mov_b64_e32 v[122:123], 0
	v_mov_b64_e32 v[124:125], 0
	v_mov_b64_e32 v[126:127], 0
	s_addc_u32 s49, s3, 0
	s_mov_b32 s4, 0
	s_mov_b64 s[56:57], 0x80

;     ...
;         const char* nA = has_next ? (const char*)g.A + (size_t)nxt.pm * tstepA + (size_t)nxt.pn * APN : cA; const char* nB = has_next ? (const char*)g.Bt + (size_t)nxt.pn * tstepB : cB;
;         for (int t = 0; t < nt; t += 2) {
;             const bool last = (t == nt - 2);
;             const char* a1 = cA + (size_t)(t + 1) * kstep;
;             const char* a2 = last ? nA : cA + (size_t)(t + 2) * kstep; const char* b2 = last ? nB : cB + (size_t)(t + 2) * kstep;
;             const char* a3 = a2 + kstep; const char* b3 = b2 + kstep;
;     ...
; #pragma unroll
;         for (int a = 0; a < 2; ++a)
; #pragma unroll
;             for (int b = 0; b < 2; ++b)
; #pragma unroll
;                 for (int m = 0; m < 4; ++m)
; #pragma unroll
;                     for (int n = 0; n < 2; ++n) acc[a][b][m][n] = (f32x4){0.f, 0.f, 0.f, 0.f};
;         cur = nxt; cA = nA; cB = nB; ++ui;
.LBB0_551:
	s_ashr_i32 s21, s20, 31
	s_lshl_b64 s[24:25], s[20:21], 19
	v_readlane_b32 s52, v254, 28
	v_readlane_b32 s53, v254, 29
	s_add_u32 s24, s52, s24
	s_addc_u32 s25, s53, s25
	s_andn2_b64 vcc, exec, s[8:9]
	s_waitcnt lgkmcnt(0)
	s_cbranch_vccnz .Lzskip_7
	s_and_b64 s[12:13], s[12:13], exec
	s_cselect_b32 s21, s25, s29
	s_cselect_b32 s51, s24, s28
	s_add_u32 s12, s28, 0x40080
	s_addc_u32 s13, s29, 0
	s_add_u32 s28, s26, 0x100
	v_mov_b64_e32 v[0:1], 0
	v_mov_b64_e32 v[2:3], 0
	v_mov_b64_e32 v[4:5], 0
	v_mov_b64_e32 v[6:7], 0
	v_mov_b64_e32 v[8:9], 0
	v_mov_b64_e32 v[10:11], 0
	v_mov_b64_e32 v[12:13], 0
	v_mov_b64_e32 v[14:15], 0
	v_mov_b64_e32 v[16:17], 0
	v_mov_b64_e32 v[18:19], 0
	v_mov_b64_e32 v[20:21], 0
	v_mov_b64_e32 v[22:23], 0
	v_mov_b64_e32 v[24:25], 0
	v_mov_b64_e32 v[26:27], 0
	v_mov_b64_e32 v[28:29], 0
	v_mov_b64_e32 v[30:31], 0
	v_mov_b64_e32 v[32:33], 0
	v_mov_b64_e32 v[34:35], 0
	v_mov_b64_e32 v[36:37], 0
	v_mov_b64_e32 v[38:39], 0
	v_mov_b64_e32 v[40:41], 0
	v_mov_b64_e32 v[42:43], 0
	v_mov_b64_e32 v[44:45], 0
	v_mov_b64_e32 v[46:47], 0
	v_mov_b64_e32 v[48:49], 0
	v_mov_b64_e32 v[50:51], 0
	v_mov_b64_e32 v[52:53], 0
	v_mov_b64_e32 v[54:55], 0
	v_mov_b64_e32 v[56:57], 0
	v_mov_b64_e32 v[58:59], 0
	v_mov_b64_e32 v[60:61], 0
	v_mov_b64_e32 v[62:63], 0
	v_mov_b64_e32 v[64:65], 0
	v_mov_b64_e32 v[66:67], 0
	v_mov_b64_e32 v[68:69], 0
	v_mov_b64_e32 v[70:71], 0
	v_mov_b64_e32 v[72:73], 0
	v_mov_b64_e32 v[74:75], 0
	v_mov_b64_e32 v[76:77], 0
	v_mov_b64_e32 v[78:79], 0
	v_mov_b64_e32 v[80:81], 0
	v_mov_b64_e32 v[82:83], 0
	v_mov_b64_e32 v[84:85], 0
	v_mov_b64_e32 v[86:87], 0
	v_mov_b64_e32 v[88:89], 0
	v_mov_b64_e32 v[90:91], 0
	v_mov_b64_e32 v[92:93], 0
	v_mov_b64_e32 v[94:95], 0
	v_mov_b64_e32 v[96:97], 0
	v_mov_b64_e32 v[98:99], 0
	v_mov_b64_e32 v[100:101], 0
	v_mov_b64_e32 v[102:103], 0
	v_mov_b64_e32 v[104:105], 0
	v_mov_b64_e32 v[106:107], 0
	v_mov_b64_e32 v[108:109], 0
	v_mov_b64_e32 v[110:111], 0
	v_mov_b64_e32 v[112:113], 0
	v_mov_b64_e32 v[114:115], 0
	v_mov_b64_e32 v[116:117], 0
	v_mov_b64_e32 v[118:119], 0
	v_mov_b64_e32 v[120:121], 0
	v_mov_b64_e32 v[122:123], 0
	v_mov_b64_e32 v[124:125], 0
	v_mov_b64_e32 v[126:127], 0
	s_addc_u32 s29, s27, 0
	s_mov_b32 s26, 0
	s_mov_b64 s[58:59], 0x80
